# out-proj mid-K hook reads its per-row statistics from an LDS stage filled by LDS-DMA at tile start (variant l>0)
# speedup vs baseline: 1.1193x; 1.0027x over previous
.LBB0_520:
	v_readlane_b32 s12, v254, 31
	v_readlane_b32 s13, v254, 32
	v_readlane_b32 s2, v254, 29
	v_readlane_b32 s3, v254, 30
	v_mbcnt_lo_u32_b32 v0, -1, 0
	v_mbcnt_hi_u32_b32 v0, -1, v0
	v_lshlrev_b32_e32 v0, 4, v0
	s_lshr_b32 s1, s85, 6
	s_lshl_b32 s14, s1, 10
	s_lshl_b32 s15, s52, 13
	s_add_i32 s15, s15, s14
	v_add_u32_e32 v1, s15, v0
	s_add_i32 m0, s14, 0x21010
	s_nop 0
	global_load_lds_dwordx4 v1, s[12:13]
	s_cmp_lt_u32 s1, 4
	s_cbranch_scc0 .Lhk_skipA
	s_lshl_b32 s15, s52, 12
	s_add_i32 s15, s15, s14
	v_add_u32_e32 v1, s15, v0
	s_add_i32 m0, s14, 0x23010
	s_nop 0
	global_load_lds_dwordx4 v1, s[2:3]

.LBB0_521:
	s_add_i32 s92, 0, 0x10000
	v_add_u32_e32 v213, s92, v210
	ds_read_b128 v[128:131], v213
	ds_read_b128 v[140:143], v213 offset:1024
	ds_read_b128 v[144:147], v213 offset:2048
	ds_read_b128 v[148:151], v213 offset:3072
	v_lshl_add_u64 v[190:191], v[132:133], 0, s[44:45]
	s_add_i32 s90, s79, 0xc000
	v_lshl_add_u64 v[194:195], v[190:191], 0, s[18:19]
	s_mov_b32 m0, s90
	ds_read_b128 v[152:155], v211
	ds_read_b128 v[156:159], v211 offset:1024
	ds_read_b128 v[160:163], v211 offset:2048
	ds_read_b128 v[164:167], v211 offset:3072
	ds_read_b128 v[168:171], v211 offset:4096
	ds_read_b128 v[172:175], v211 offset:5120
	ds_read_b128 v[200:203], v211 offset:6144
	ds_read_b128 v[216:219], v211 offset:7168
	global_load_lds_dwordx4 v[194:195], off
	v_lshl_add_u64 v[194:195], v[134:135], 0, s[44:45]
	s_add_i32 s91, s79, 0xe000
	v_lshl_add_u64 v[204:205], v[194:195], 0, s[18:19]
	s_mov_b32 m0, s91
	s_nop 0
	global_load_lds_dwordx4 v[204:205], off
	s_waitcnt lgkmcnt(8)
	s_barrier
	s_waitcnt lgkmcnt(0)
	s_setprio 1
	s_waitcnt lgkmcnt(0)
	v_mfma_f32_16x16x32_bf16 v[60:63], v[128:131], v[152:155], v[60:63]
	v_mfma_f32_16x16x32_bf16 v[56:59], v[144:147], v[152:155], v[56:59]
	v_mfma_f32_16x16x32_bf16 v[92:95], v[128:131], v[160:163], v[92:95]
	v_mfma_f32_16x16x32_bf16 v[88:91], v[144:147], v[160:163], v[88:91]
	v_mfma_f32_16x16x32_bf16 v[124:127], v[128:131], v[168:171], v[124:127]
	v_mfma_f32_16x16x32_bf16 v[120:123], v[144:147], v[168:171], v[120:123]
	v_mfma_f32_16x16x32_bf16 v[108:111], v[128:131], v[200:203], v[108:111]
	v_mfma_f32_16x16x32_bf16 v[104:107], v[144:147], v[200:203], v[104:107]
	v_mfma_f32_16x16x32_bf16 v[60:63], v[140:143], v[156:159], v[60:63]
	v_mfma_f32_16x16x32_bf16 v[56:59], v[148:151], v[156:159], v[56:59]
	v_mfma_f32_16x16x32_bf16 v[92:95], v[140:143], v[164:167], v[92:95]
	v_mfma_f32_16x16x32_bf16 v[88:91], v[148:151], v[164:167], v[88:91]
	v_mfma_f32_16x16x32_bf16 v[124:127], v[140:143], v[172:175], v[124:127]
	v_mfma_f32_16x16x32_bf16 v[120:123], v[148:151], v[172:175], v[120:123]
	v_mfma_f32_16x16x32_bf16 v[108:111], v[140:143], v[216:219], v[108:111]
	v_mfma_f32_16x16x32_bf16 v[104:107], v[148:151], v[216:219], v[104:107]
	s_setprio 0
	s_barrier
	s_add_i32 s94, 0, 0x14000
	v_lshl_add_u64 v[204:205], v[136:137], 0, s[44:45]
	s_add_i32 s92, s92, s77
	v_add_u32_e32 v214, s94, v210
	v_lshl_add_u64 v[236:237], v[204:205], 0, s[24:25]
	s_mov_b32 m0, s92
	v_lshl_add_u64 v[238:239], v[138:139], 0, s[44:45]
	s_add_i32 s93, s92, 0x2000
	ds_read_b128 v[220:223], v214
	ds_read_b128 v[224:227], v214 offset:1024
	ds_read_b128 v[228:231], v214 offset:2048
	ds_read_b128 v[232:235], v214 offset:3072
	global_load_lds_dwordx4 v[236:237], off
	v_lshl_add_u64 v[236:237], v[238:239], 0, s[24:25]
	s_mov_b32 m0, s93
	s_nop 0
	global_load_lds_dwordx4 v[236:237], off
	s_barrier
	s_waitcnt lgkmcnt(0)
	s_setprio 1
	s_waitcnt lgkmcnt(0)
	v_mfma_f32_16x16x32_bf16 v[52:55], v[220:223], v[152:155], v[52:55]
	v_mfma_f32_16x16x32_bf16 v[48:51], v[228:231], v[152:155], v[48:51]
	v_mfma_f32_16x16x32_bf16 v[84:87], v[220:223], v[160:163], v[84:87]
	v_mfma_f32_16x16x32_bf16 v[80:83], v[228:231], v[160:163], v[80:83]
	v_mfma_f32_16x16x32_bf16 v[116:119], v[220:223], v[168:171], v[116:119]
	v_mfma_f32_16x16x32_bf16 v[112:115], v[228:231], v[168:171], v[112:115]
	v_mfma_f32_16x16x32_bf16 v[100:103], v[220:223], v[200:203], v[100:103]
	v_mfma_f32_16x16x32_bf16 v[96:99], v[228:231], v[200:203], v[96:99]
	v_mfma_f32_16x16x32_bf16 v[52:55], v[224:227], v[156:159], v[52:55]
	v_mfma_f32_16x16x32_bf16 v[48:51], v[232:235], v[156:159], v[48:51]
	v_mfma_f32_16x16x32_bf16 v[84:87], v[224:227], v[164:167], v[84:87]
	v_mfma_f32_16x16x32_bf16 v[80:83], v[232:235], v[164:167], v[80:83]
	v_mfma_f32_16x16x32_bf16 v[116:119], v[224:227], v[172:175], v[116:119]
	v_mfma_f32_16x16x32_bf16 v[112:115], v[232:235], v[172:175], v[112:115]
	v_mfma_f32_16x16x32_bf16 v[100:103], v[224:227], v[216:219], v[100:103]
	v_mfma_f32_16x16x32_bf16 v[96:99], v[232:235], v[216:219], v[96:99]
	s_setprio 0
	s_mov_b32 m0, s79
	v_lshl_add_u64 v[236:237], v[190:191], 0, s[24:25]
	s_barrier
	ds_read_b128 v[152:155], v211 offset:16384
	ds_read_b128 v[156:159], v211 offset:17408
	ds_read_b128 v[160:163], v211 offset:18432
	ds_read_b128 v[164:167], v211 offset:19456
	ds_read_b128 v[168:171], v211 offset:20480
	ds_read_b128 v[172:175], v211 offset:21504
	ds_read_b128 v[200:203], v211 offset:22528
	ds_read_b128 v[216:219], v211 offset:23552
	global_load_lds_dwordx4 v[236:237], off
	v_lshl_add_u64 v[236:237], v[194:195], 0, s[24:25]
	s_mov_b32 m0, s80
	s_nop 0
	global_load_lds_dwordx4 v[236:237], off
	s_barrier
	s_waitcnt lgkmcnt(0)
	s_setprio 1
	s_waitcnt lgkmcnt(0)
	v_mfma_f32_16x16x32_bf16 v[76:79], v[128:131], v[152:155], v[76:79]
	v_mfma_f32_16x16x32_bf16 v[72:75], v[144:147], v[152:155], v[72:75]
	v_mfma_f32_16x16x32_bf16 v[44:47], v[128:131], v[160:163], v[44:47]
	v_mfma_f32_16x16x32_bf16 v[40:43], v[144:147], v[160:163], v[40:43]
	v_mfma_f32_16x16x32_bf16 v[28:31], v[128:131], v[168:171], v[28:31]
	v_mfma_f32_16x16x32_bf16 v[24:27], v[144:147], v[168:171], v[24:27]
	v_mfma_f32_16x16x32_bf16 v[12:15], v[128:131], v[200:203], v[12:15]
	v_mfma_f32_16x16x32_bf16 v[8:11], v[144:147], v[200:203], v[8:11]
	v_mfma_f32_16x16x32_bf16 v[76:79], v[140:143], v[156:159], v[76:79]
	v_mfma_f32_16x16x32_bf16 v[72:75], v[148:151], v[156:159], v[72:75]
	v_mfma_f32_16x16x32_bf16 v[44:47], v[140:143], v[164:167], v[44:47]
	v_mfma_f32_16x16x32_bf16 v[40:43], v[148:151], v[164:167], v[40:43]
	v_mfma_f32_16x16x32_bf16 v[28:31], v[140:143], v[172:175], v[28:31]
	v_mfma_f32_16x16x32_bf16 v[24:27], v[148:151], v[172:175], v[24:27]
	v_mfma_f32_16x16x32_bf16 v[12:15], v[140:143], v[216:219], v[12:15]
	v_mfma_f32_16x16x32_bf16 v[8:11], v[148:151], v[216:219], v[8:11]
	s_setprio 0
	s_barrier
	s_add_i32 s94, s94, s77
	v_lshl_add_u64 v[128:129], v[204:205], 0, s[28:29]
	s_mov_b32 m0, s94
	s_add_i32 s95, s94, 0x2000
	global_load_lds_dwordx4 v[128:129], off
	v_lshl_add_u64 v[128:129], v[238:239], 0, s[28:29]
	s_mov_b32 m0, s95
	s_nop 0
	global_load_lds_dwordx4 v[128:129], off
	s_waitcnt vmcnt(6)
	s_barrier
	s_setprio 1
	v_mfma_f32_16x16x32_bf16 v[68:71], v[220:223], v[152:155], v[68:71]
	v_mfma_f32_16x16x32_bf16 v[64:67], v[228:231], v[152:155], v[64:67]
	v_mfma_f32_16x16x32_bf16 v[36:39], v[220:223], v[160:163], v[36:39]
	v_mfma_f32_16x16x32_bf16 v[32:35], v[228:231], v[160:163], v[32:35]
	v_mfma_f32_16x16x32_bf16 v[20:23], v[220:223], v[168:171], v[20:23]
	v_mfma_f32_16x16x32_bf16 v[16:19], v[228:231], v[168:171], v[16:19]
	v_mfma_f32_16x16x32_bf16 v[4:7], v[220:223], v[200:203], v[4:7]
	v_mfma_f32_16x16x32_bf16 v[0:3], v[228:231], v[200:203], v[0:3]
	v_mfma_f32_16x16x32_bf16 v[68:71], v[224:227], v[156:159], v[68:71]
	v_mfma_f32_16x16x32_bf16 v[64:67], v[232:235], v[156:159], v[64:67]
	v_mfma_f32_16x16x32_bf16 v[36:39], v[224:227], v[164:167], v[36:39]
	v_mfma_f32_16x16x32_bf16 v[32:35], v[232:235], v[164:167], v[32:35]
	v_mfma_f32_16x16x32_bf16 v[20:23], v[224:227], v[172:175], v[20:23]
	v_mfma_f32_16x16x32_bf16 v[16:19], v[232:235], v[172:175], v[16:19]
	v_mfma_f32_16x16x32_bf16 v[4:7], v[224:227], v[216:219], v[4:7]
	v_mfma_f32_16x16x32_bf16 v[0:3], v[232:235], v[216:219], v[0:3]
	s_setprio 0
	s_add_i32 s96, 0, 0x18000
	v_add_u32_e32 v215, s96, v210
	s_barrier
	ds_read_b128 v[128:131], v215
	ds_read_b128 v[140:143], v215 offset:1024
	ds_read_b128 v[144:147], v215 offset:2048
	ds_read_b128 v[148:151], v215 offset:3072
	s_mov_b32 m0, s81
	v_lshl_add_u64 v[216:217], v[190:191], 0, s[28:29]
	ds_read_b128 v[152:155], v211 offset:32768
	ds_read_b128 v[156:159], v211 offset:33792
	ds_read_b128 v[160:163], v211 offset:34816
	ds_read_b128 v[164:167], v211 offset:35840
	ds_read_b128 v[168:171], v211 offset:36864
	ds_read_b128 v[172:175], v211 offset:37888
	ds_read_b128 v[200:203], v211 offset:38912
	ds_read_b128 v[218:221], v211 offset:39936
	global_load_lds_dwordx4 v[216:217], off
	v_lshl_add_u64 v[216:217], v[194:195], 0, s[28:29]
	s_mov_b32 m0, s82
	s_nop 0
	global_load_lds_dwordx4 v[216:217], off
	s_waitcnt lgkmcnt(8)
	s_barrier
	s_waitcnt lgkmcnt(0)
	s_setprio 1
	s_waitcnt lgkmcnt(0)
	v_mfma_f32_16x16x32_bf16 v[60:63], v[128:131], v[152:155], v[60:63]
	v_mfma_f32_16x16x32_bf16 v[56:59], v[144:147], v[152:155], v[56:59]
	v_mfma_f32_16x16x32_bf16 v[92:95], v[128:131], v[160:163], v[92:95]
	v_mfma_f32_16x16x32_bf16 v[88:91], v[144:147], v[160:163], v[88:91]
	v_mfma_f32_16x16x32_bf16 v[124:127], v[128:131], v[168:171], v[124:127]
	v_mfma_f32_16x16x32_bf16 v[120:123], v[144:147], v[168:171], v[120:123]
	v_mfma_f32_16x16x32_bf16 v[108:111], v[128:131], v[200:203], v[108:111]
	v_mfma_f32_16x16x32_bf16 v[104:107], v[144:147], v[200:203], v[104:107]
	v_mfma_f32_16x16x32_bf16 v[60:63], v[140:143], v[156:159], v[60:63]
	v_mfma_f32_16x16x32_bf16 v[56:59], v[148:151], v[156:159], v[56:59]
	v_mfma_f32_16x16x32_bf16 v[92:95], v[140:143], v[164:167], v[92:95]
	v_mfma_f32_16x16x32_bf16 v[88:91], v[148:151], v[164:167], v[88:91]
	v_mfma_f32_16x16x32_bf16 v[124:127], v[140:143], v[172:175], v[124:127]
	v_mfma_f32_16x16x32_bf16 v[120:123], v[148:151], v[172:175], v[120:123]
	v_mfma_f32_16x16x32_bf16 v[108:111], v[140:143], v[218:221], v[108:111]
	v_mfma_f32_16x16x32_bf16 v[104:107], v[148:151], v[218:221], v[104:107]
	s_setprio 0
	s_barrier
	s_add_i32 s61, 0, 0x1c000
	s_add_i32 s96, s96, s77
	v_add_u32_e32 v216, s61, v210
	v_lshl_add_u64 v[240:241], v[204:205], 0, s[50:51]
	s_mov_b32 m0, s96
	s_add_i32 s60, s96, 0x2000
	ds_read_b128 v[222:225], v216
	ds_read_b128 v[226:229], v216 offset:1024
	ds_read_b128 v[230:233], v216 offset:2048
	ds_read_b128 v[234:237], v216 offset:3072
	global_load_lds_dwordx4 v[240:241], off
	v_lshl_add_u64 v[240:241], v[238:239], 0, s[50:51]
	s_mov_b32 m0, s60
	s_nop 0
	global_load_lds_dwordx4 v[240:241], off
	s_barrier
	s_waitcnt lgkmcnt(0)
	s_setprio 1
	s_waitcnt lgkmcnt(0)
	v_mfma_f32_16x16x32_bf16 v[52:55], v[222:225], v[152:155], v[52:55]
	v_mfma_f32_16x16x32_bf16 v[48:51], v[230:233], v[152:155], v[48:51]
	v_mfma_f32_16x16x32_bf16 v[84:87], v[222:225], v[160:163], v[84:87]
	v_mfma_f32_16x16x32_bf16 v[80:83], v[230:233], v[160:163], v[80:83]
	v_mfma_f32_16x16x32_bf16 v[116:119], v[222:225], v[168:171], v[116:119]
	v_mfma_f32_16x16x32_bf16 v[112:115], v[230:233], v[168:171], v[112:115]
	v_mfma_f32_16x16x32_bf16 v[100:103], v[222:225], v[200:203], v[100:103]
	v_mfma_f32_16x16x32_bf16 v[96:99], v[230:233], v[200:203], v[96:99]
	v_mfma_f32_16x16x32_bf16 v[52:55], v[226:229], v[156:159], v[52:55]
	v_mfma_f32_16x16x32_bf16 v[48:51], v[234:237], v[156:159], v[48:51]
	v_mfma_f32_16x16x32_bf16 v[84:87], v[226:229], v[164:167], v[84:87]
	v_mfma_f32_16x16x32_bf16 v[80:83], v[234:237], v[164:167], v[80:83]
	v_mfma_f32_16x16x32_bf16 v[116:119], v[226:229], v[172:175], v[116:119]
	v_mfma_f32_16x16x32_bf16 v[112:115], v[234:237], v[172:175], v[112:115]
	v_mfma_f32_16x16x32_bf16 v[100:103], v[226:229], v[218:221], v[100:103]
	v_mfma_f32_16x16x32_bf16 v[96:99], v[234:237], v[218:221], v[96:99]
	s_setprio 0
	s_mov_b32 m0, s87
	v_lshl_add_u64 v[190:191], v[190:191], 0, s[50:51]
	s_barrier
	ds_read_b128 v[152:155], v211 offset:49152
	ds_read_b128 v[156:159], v211 offset:50176
	ds_read_b128 v[160:163], v211 offset:51200
	ds_read_b128 v[164:167], v211 offset:52224
	ds_read_b128 v[168:171], v211 offset:53248
	ds_read_b128 v[172:175], v211 offset:54272
	ds_read_b128 v[200:203], v211 offset:55296
	ds_read_b128 v[218:221], v211 offset:56320
	global_load_lds_dwordx4 v[190:191], off
	v_lshl_add_u64 v[190:191], v[194:195], 0, s[50:51]
	s_mov_b32 m0, s88
	s_nop 0
	global_load_lds_dwordx4 v[190:191], off
	s_barrier
	s_waitcnt lgkmcnt(0)
	s_setprio 1
	s_waitcnt lgkmcnt(0)
	v_mfma_f32_16x16x32_bf16 v[76:79], v[128:131], v[152:155], v[76:79]
	v_mfma_f32_16x16x32_bf16 v[72:75], v[144:147], v[152:155], v[72:75]
	v_mfma_f32_16x16x32_bf16 v[44:47], v[128:131], v[160:163], v[44:47]
	v_mfma_f32_16x16x32_bf16 v[40:43], v[144:147], v[160:163], v[40:43]
	v_mfma_f32_16x16x32_bf16 v[28:31], v[128:131], v[168:171], v[28:31]
	v_mfma_f32_16x16x32_bf16 v[24:27], v[144:147], v[168:171], v[24:27]
	v_mfma_f32_16x16x32_bf16 v[12:15], v[128:131], v[200:203], v[12:15]
	v_mfma_f32_16x16x32_bf16 v[8:11], v[144:147], v[200:203], v[8:11]
	v_mfma_f32_16x16x32_bf16 v[76:79], v[140:143], v[156:159], v[76:79]
	v_mfma_f32_16x16x32_bf16 v[72:75], v[148:151], v[156:159], v[72:75]
	v_mfma_f32_16x16x32_bf16 v[44:47], v[140:143], v[164:167], v[44:47]
	v_mfma_f32_16x16x32_bf16 v[40:43], v[148:151], v[164:167], v[40:43]
	v_mfma_f32_16x16x32_bf16 v[28:31], v[140:143], v[172:175], v[28:31]
	v_mfma_f32_16x16x32_bf16 v[24:27], v[148:151], v[172:175], v[24:27]
	v_mfma_f32_16x16x32_bf16 v[12:15], v[140:143], v[218:221], v[12:15]
	v_mfma_f32_16x16x32_bf16 v[8:11], v[148:151], v[218:221], v[8:11]
	s_setprio 0
	s_barrier
	s_add_i32 s61, s61, s77
	v_lshl_add_u64 v[128:129], v[204:205], 0, s[6:7]
	s_mov_b32 m0, s61
	s_add_i32 s49, s61, 0x2000
	global_load_lds_dwordx4 v[128:129], off
	v_lshl_add_u64 v[128:129], v[238:239], 0, s[6:7]
	s_mov_b32 m0, s49
	s_nop 0
	global_load_lds_dwordx4 v[128:129], off
	s_waitcnt vmcnt(6)
	s_barrier
	s_setprio 1
	v_mfma_f32_16x16x32_bf16 v[68:71], v[222:225], v[152:155], v[68:71]
	v_mfma_f32_16x16x32_bf16 v[64:67], v[230:233], v[152:155], v[64:67]
	v_mfma_f32_16x16x32_bf16 v[36:39], v[222:225], v[160:163], v[36:39]
	v_mfma_f32_16x16x32_bf16 v[32:35], v[230:233], v[160:163], v[32:35]
	v_mfma_f32_16x16x32_bf16 v[20:23], v[222:225], v[168:171], v[20:23]
	v_mfma_f32_16x16x32_bf16 v[16:19], v[230:233], v[168:171], v[16:19]
	v_mfma_f32_16x16x32_bf16 v[4:7], v[222:225], v[200:203], v[4:7]
	v_mfma_f32_16x16x32_bf16 v[0:3], v[230:233], v[200:203], v[0:3]
	v_mfma_f32_16x16x32_bf16 v[68:71], v[226:229], v[156:159], v[68:71]
	v_mfma_f32_16x16x32_bf16 v[64:67], v[234:237], v[156:159], v[64:67]
	v_mfma_f32_16x16x32_bf16 v[36:39], v[226:229], v[164:167], v[36:39]
	v_mfma_f32_16x16x32_bf16 v[32:35], v[234:237], v[164:167], v[32:35]
	v_mfma_f32_16x16x32_bf16 v[20:23], v[226:229], v[172:175], v[20:23]
	v_mfma_f32_16x16x32_bf16 v[16:19], v[234:237], v[172:175], v[16:19]
	v_mfma_f32_16x16x32_bf16 v[4:7], v[226:229], v[218:221], v[4:7]
	v_mfma_f32_16x16x32_bf16 v[0:3], v[234:237], v[218:221], v[0:3]
	s_setprio 0
	s_add_i32 s39, s39, 2
	s_add_u32 s44, s44, 0x100
	s_addc_u32 s45, s45, 0
	s_cmp_gt_u32 s39, 13
	s_barrier
	s_cbranch_scc0 .LBB0_521
	s_lshl_b32 s52, s52, 8
	s_lshl_b32 s12, s52, 5
	s_sub_i32 s12, 0x21010, s12
	s_lshl_b32 s2, s52, 4
	s_sub_i32 s2, 0x23010, s2
	s_add_i32 s1, s52, s86
	v_mov_b32_e32 v128, v208
	v_bfe_u32 v154, v128, 4, 2
	v_and_or_b32 v155, v128, 15, s1
	v_lshlrev_b32_e32 v157, 1, v154
	v_lshl_or_b32 v128, v155, 3, v157
	v_ashrrev_i32_e32 v129, 31, v128
	v_lshl_add_u32 v128, v128, 2, s12
	ds_read_b64 v[128:129], v128
	v_or_b32_e32 v130, 16, v155
	s_mov_b32 s14, 0x358637bd
	s_waitcnt lgkmcnt(0)
	v_pk_add_f32 v[158:159], v[128:129], v[128:129] op_sel:[0,1] op_sel_hi:[1,0]
	v_lshl_or_b32 v128, v155, 2, v154
	v_ashrrev_i32_e32 v129, 31, v128
	v_lshl_add_u32 v128, v128, 2, s2
	ds_read_b32 v160, v128
	v_lshl_or_b32 v128, v130, 3, v157
	v_ashrrev_i32_e32 v129, 31, v128
	v_lshl_add_u32 v128, v128, 2, s12
	ds_read_b64 v[128:129], v128
	ds_bpermute_b32 v163, v207, v158
	v_mov_b32_e32 v161, v158
	s_waitcnt lgkmcnt(0)
	ds_bpermute_b32 v162, v207, v160
	v_pk_add_f32 v[148:149], v[128:129], v[128:129] op_sel:[0,1] op_sel_hi:[1,0]
	v_lshl_or_b32 v128, v130, 2, v154
	v_ashrrev_i32_e32 v129, 31, v128
	v_lshl_add_u32 v128, v128, 2, s2
	v_or_b32_e32 v130, 32, v155
	ds_read_b32 v150, v128
	v_lshl_or_b32 v128, v130, 3, v157
	v_ashrrev_i32_e32 v129, 31, v128
	v_lshl_add_u32 v128, v128, 2, s12
	ds_read_b64 v[128:129], v128
	s_waitcnt lgkmcnt(0)
	v_pk_add_f32 v[158:159], v[160:161], v[162:163]
	ds_bpermute_b32 v161, v206, v159
	ds_bpermute_b32 v160, v206, v158
	ds_bpermute_b32 v153, v207, v148
	v_mov_b32_e32 v151, v148
	s_waitcnt lgkmcnt(1)
	v_pk_add_f32 v[160:161], v[158:159], v[160:161]
	v_mov_b64_e32 v[158:159], s[14:15]
	s_mov_b32 s14, 0x3b000000
	s_mov_b32 s15, 0x3a800000
	v_pk_fma_f32 v[160:161], v[160:161], s[14:15], v[158:159] op_sel_hi:[1,1,0]
	s_waitcnt lgkmcnt(0)
	ds_bpermute_b32 v152, v207, v150
	v_cmp_gt_f32_e64 s[46:47], s33, v161
	v_cmp_gt_f32_e64 s[44:45], s33, v160
	s_waitcnt lgkmcnt(0)
	v_pk_add_f32 v[144:145], v[128:129], v[128:129] op_sel:[0,1] op_sel_hi:[1,0]
	v_lshl_or_b32 v128, v130, 2, v154
	v_ashrrev_i32_e32 v129, 31, v128
	v_lshl_add_u32 v128, v128, 2, s2
	v_or_b32_e32 v130, 48, v155
	ds_read_b32 v142, v128
	v_lshl_or_b32 v128, v130, 3, v157
	v_ashrrev_i32_e32 v129, 31, v128
	v_lshl_add_u32 v128, v128, 2, s12
	ds_read_b64 v[128:129], v128
	v_lshl_or_b32 v130, v130, 2, v154
	v_ashrrev_i32_e32 v131, 31, v130
	v_lshl_add_u32 v130, v130, 2, s2
	ds_read_b32 v130, v130
	s_waitcnt lgkmcnt(0)
	v_pk_add_f32 v[148:149], v[150:151], v[152:153]
	ds_bpermute_b32 v151, v206, v149
	ds_bpermute_b32 v150, v206, v148
	ds_bpermute_b32 v147, v207, v144
	s_waitcnt lgkmcnt(1)
	v_pk_add_f32 v[148:149], v[148:149], v[150:151]
	s_nop 0
	v_pk_fma_f32 v[148:149], v[148:149], s[14:15], v[158:159] op_sel_hi:[1,1,0]
	s_waitcnt lgkmcnt(0)
	ds_bpermute_b32 v146, v207, v142
	s_waitcnt lgkmcnt(0)
	v_pk_add_f32 v[128:129], v[128:129], v[128:129] op_sel:[0,1] op_sel_hi:[1,0]
	s_nop 0
	v_mul_f32_e32 v129, 0x4b800000, v161
	v_cndmask_b32_e64 v129, v161, v129, s[46:47]
	v_rsq_f32_e32 v129, v129
	ds_bpermute_b32 v141, v207, v128
	s_waitcnt lgkmcnt(0)
	ds_bpermute_b32 v140, v207, v130
	v_mul_f32_e32 v131, 0x45800000, v129
	v_cndmask_b32_e64 v129, v129, v131, s[46:47]
	v_mul_f32_e32 v131, 0x4b800000, v160
	v_cndmask_b32_e64 v131, v160, v131, s[44:45]
	v_rsq_f32_e32 v131, v131
	v_mul_f32_e32 v129, v160, v129
	v_cmp_gt_f32_e64 s[46:47], s33, v149
	v_mul_f32_e32 v143, 0x45800000, v131
	v_cndmask_b32_e64 v156, v131, v143, s[44:45]
	v_mul_f32_e32 v160, v129, v156
	v_mul_f32_e32 v129, 0x4b800000, v149
	v_cndmask_b32_e64 v129, v149, v129, s[46:47]
	v_rsq_f32_e32 v129, v129
	v_cmp_gt_f32_e64 s[44:45], s33, v148
	v_pk_mul_f32 v[62:63], v[62:63], v[160:161] op_sel_hi:[1,0]
	v_pk_mul_f32 v[60:61], v[60:61], v[160:161] op_sel_hi:[1,0]
	v_mul_f32_e32 v131, 0x45800000, v129
	v_cndmask_b32_e64 v129, v129, v131, s[46:47]
	v_mul_f32_e32 v131, 0x4b800000, v148
	v_cndmask_b32_e64 v131, v148, v131, s[44:45]
	v_rsq_f32_e32 v131, v131
	v_mul_f32_e32 v129, v148, v129
	v_pk_mul_f32 v[58:59], v[58:59], v[160:161] op_sel_hi:[1,0]
	v_pk_mul_f32 v[56:57], v[56:57], v[160:161] op_sel_hi:[1,0]
	v_mul_f32_e32 v143, 0x45800000, v131
	v_cndmask_b32_e64 v188, v131, v143, s[44:45]
	v_mov_b32_e32 v143, v144
	s_waitcnt lgkmcnt(2)
	v_pk_add_f32 v[142:143], v[142:143], v[146:147]
	ds_bpermute_b32 v145, v206, v143
	ds_bpermute_b32 v144, v206, v142
	v_mul_f32_e32 v148, v129, v188
	v_pk_mul_f32 v[54:55], v[54:55], v[160:161] op_sel_hi:[1,0]
	v_pk_mul_f32 v[52:53], v[52:53], v[160:161] op_sel_hi:[1,0]
	v_pk_mul_f32 v[50:51], v[50:51], v[160:161] op_sel_hi:[1,0]
	s_waitcnt lgkmcnt(0)
	v_pk_add_f32 v[142:143], v[142:143], v[144:145]
	v_pk_mul_f32 v[48:49], v[48:49], v[160:161] op_sel_hi:[1,0]
	v_pk_fma_f32 v[142:143], v[142:143], s[14:15], v[158:159] op_sel_hi:[1,1,0]
	v_pk_mul_f32 v[94:95], v[94:95], v[148:149] op_sel_hi:[1,0]
	v_mul_f32_e32 v129, 0x4b800000, v143
	v_cmp_gt_f32_e64 s[46:47], s33, v143
	v_cmp_gt_f32_e64 s[44:45], s33, v142
	v_pk_mul_f32 v[92:93], v[92:93], v[148:149] op_sel_hi:[1,0]
	v_cndmask_b32_e64 v129, v143, v129, s[46:47]
	v_rsq_f32_e32 v129, v129
	v_pk_mul_f32 v[90:91], v[90:91], v[148:149] op_sel_hi:[1,0]
	v_pk_mul_f32 v[88:89], v[88:89], v[148:149] op_sel_hi:[1,0]
	v_pk_mul_f32 v[86:87], v[86:87], v[148:149] op_sel_hi:[1,0]
	v_mul_f32_e32 v131, 0x45800000, v129
	v_cndmask_b32_e64 v129, v129, v131, s[46:47]
	v_mul_f32_e32 v131, 0x4b800000, v142
	v_cndmask_b32_e64 v131, v142, v131, s[44:45]
	v_rsq_f32_e32 v131, v131
	v_mul_f32_e32 v129, v142, v129
	v_pk_mul_f32 v[84:85], v[84:85], v[148:149] op_sel_hi:[1,0]
	v_pk_mul_f32 v[82:83], v[82:83], v[148:149] op_sel_hi:[1,0]
	v_mul_f32_e32 v143, 0x45800000, v131
	v_cndmask_b32_e64 v190, v131, v143, s[44:45]
	v_mov_b32_e32 v131, v128
	v_mul_f32_e32 v142, v129, v190
	v_pk_add_f32 v[128:129], v[130:131], v[140:141]
	ds_bpermute_b32 v131, v206, v129
	ds_bpermute_b32 v130, v206, v128
	v_pk_mul_f32 v[80:81], v[80:81], v[148:149] op_sel_hi:[1,0]
	v_pk_mul_f32 v[126:127], v[126:127], v[142:143] op_sel_hi:[1,0]
	v_pk_mul_f32 v[124:125], v[124:125], v[142:143] op_sel_hi:[1,0]
	v_pk_mul_f32 v[122:123], v[122:123], v[142:143] op_sel_hi:[1,0]
	s_waitcnt lgkmcnt(0)
	v_pk_add_f32 v[128:129], v[128:129], v[130:131]
	v_pk_mul_f32 v[120:121], v[120:121], v[142:143] op_sel_hi:[1,0]
	v_pk_fma_f32 v[128:129], v[128:129], s[14:15], v[158:159] op_sel_hi:[1,1,0]
	v_pk_mul_f32 v[118:119], v[118:119], v[142:143] op_sel_hi:[1,0]
	v_mul_f32_e32 v130, 0x4b800000, v129
	v_cmp_gt_f32_e64 s[46:47], s33, v129
	v_cmp_gt_f32_e64 s[44:45], s33, v128
	v_pk_mul_f32 v[116:117], v[116:117], v[142:143] op_sel_hi:[1,0]
	v_cndmask_b32_e64 v129, v129, v130, s[46:47]
	v_rsq_f32_e32 v129, v129
	v_pk_mul_f32 v[114:115], v[114:115], v[142:143] op_sel_hi:[1,0]
	v_pk_mul_f32 v[112:113], v[112:113], v[142:143] op_sel_hi:[1,0]
	v_mul_f32_e32 v130, 0x45800000, v129
	v_cndmask_b32_e64 v129, v129, v130, s[46:47]
	v_mul_f32_e32 v130, 0x4b800000, v128
	v_cndmask_b32_e64 v130, v128, v130, s[44:45]
	v_rsq_f32_e32 v130, v130
	v_mul_f32_e32 v128, v128, v129
	v_mul_f32_e32 v131, 0x45800000, v130
	v_cndmask_b32_e64 v192, v130, v131, s[44:45]
	v_mul_f32_e32 v140, v128, v192
	v_pk_mul_f32 v[130:131], v[110:111], v[140:141] op_sel_hi:[1,0]
	v_pk_mul_f32 v[128:129], v[108:109], v[140:141] op_sel_hi:[1,0]
	v_pk_mul_f32 v[110:111], v[106:107], v[140:141] op_sel_hi:[1,0]
	v_pk_mul_f32 v[108:109], v[104:105], v[140:141] op_sel_hi:[1,0]
	v_pk_mul_f32 v[106:107], v[102:103], v[140:141] op_sel_hi:[1,0]
	v_pk_mul_f32 v[104:105], v[100:101], v[140:141] op_sel_hi:[1,0]
	v_pk_mul_f32 v[102:103], v[98:99], v[140:141] op_sel_hi:[1,0]
	v_pk_mul_f32 v[100:101], v[96:97], v[140:141] op_sel_hi:[1,0]
	v_add_u32_e32 v98, 0x80, v155
	v_lshl_or_b32 v96, v98, 3, v157
	v_ashrrev_i32_e32 v97, 31, v96
	v_lshl_add_u32 v96, v96, 2, s12
	ds_read_b64 v[96:97], v96
	s_waitcnt lgkmcnt(0)
	v_pk_add_f32 v[140:141], v[96:97], v[96:97] op_sel:[0,1] op_sel_hi:[1,0]
	v_lshl_or_b32 v96, v98, 2, v154
	v_ashrrev_i32_e32 v97, 31, v96
	v_lshl_add_u32 v96, v96, 2, s2
	v_add_u32_e32 v98, 0x90, v155
	ds_read_b32 v142, v96
	v_lshl_or_b32 v96, v98, 3, v157
	v_ashrrev_i32_e32 v97, 31, v96
	v_lshl_add_u32 v96, v96, 2, s12
	ds_read_b64 v[96:97], v96
	ds_bpermute_b32 v145, v207, v140
	v_mov_b32_e32 v143, v140
	s_waitcnt lgkmcnt(0)
	ds_bpermute_b32 v144, v207, v142
	s_waitcnt lgkmcnt(0)
	v_pk_add_f32 v[168:169], v[96:97], v[96:97] op_sel:[0,1] op_sel_hi:[1,0]
	v_lshl_or_b32 v96, v98, 2, v154
	v_ashrrev_i32_e32 v97, 31, v96
	v_lshl_add_u32 v96, v96, 2, s2
	v_add_u32_e32 v98, 0xa0, v155
	ds_read_b32 v170, v96
	v_lshl_or_b32 v96, v98, 3, v157
	v_ashrrev_i32_e32 v97, 31, v96
	v_lshl_add_u32 v96, v96, 2, s12
	ds_read_b64 v[96:97], v96
	s_waitcnt lgkmcnt(0)
	v_pk_add_f32 v[140:141], v[142:143], v[144:145]
	ds_bpermute_b32 v143, v206, v141
	ds_bpermute_b32 v142, v206, v140
	ds_bpermute_b32 v173, v207, v168
	v_mov_b32_e32 v171, v168
	s_waitcnt lgkmcnt(1)
	v_pk_add_f32 v[140:141], v[140:141], v[142:143]
	s_nop 0
	v_pk_fma_f32 v[140:141], v[140:141], s[14:15], v[158:159] op_sel_hi:[1,1,0]
	s_waitcnt lgkmcnt(0)
	ds_bpermute_b32 v172, v207, v170
	v_cmp_gt_f32_e64 s[46:47], s33, v141
	v_cmp_gt_f32_e64 s[44:45], s33, v140
	s_waitcnt lgkmcnt(0)
	v_pk_add_f32 v[162:163], v[96:97], v[96:97] op_sel:[0,1] op_sel_hi:[1,0]
	v_lshl_or_b32 v96, v98, 2, v154
	v_ashrrev_i32_e32 v97, 31, v96
	v_lshl_add_u32 v96, v96, 2, s2
	v_add_u32_e32 v98, 0xb0, v155
	ds_read_b32 v164, v96
	v_lshl_or_b32 v96, v98, 3, v157
	v_ashrrev_i32_e32 v97, 31, v96
	v_lshl_add_u32 v96, v96, 2, s12
	ds_read_b64 v[96:97], v96
	v_lshl_or_b32 v98, v98, 2, v154
	v_ashrrev_i32_e32 v99, 31, v98
	v_lshl_add_u32 v98, v98, 2, s2
	ds_read_b32 v98, v98
	ds_bpermute_b32 v167, v207, v162
	v_mov_b32_e32 v165, v162
	s_waitcnt lgkmcnt(0)
	ds_bpermute_b32 v166, v207, v164
	s_waitcnt lgkmcnt(0)
	v_pk_add_f32 v[96:97], v[96:97], v[96:97] op_sel:[0,1] op_sel_hi:[1,0]
	s_nop 0
	v_mul_f32_e32 v97, 0x4b800000, v141
	v_cndmask_b32_e64 v97, v141, v97, s[46:47]
	v_rsq_f32_e32 v97, v97
	ds_bpermute_b32 v161, v207, v96
	s_waitcnt lgkmcnt(0)
	ds_bpermute_b32 v160, v207, v98
	v_mul_f32_e32 v99, 0x45800000, v97
	v_cndmask_b32_e64 v97, v97, v99, s[46:47]
	v_mul_f32_e32 v99, 0x4b800000, v140
	v_cndmask_b32_e64 v99, v140, v99, s[44:45]
	v_rsq_f32_e32 v99, v99
	v_mul_f32_e32 v97, v140, v97
	v_mul_f32_e32 v141, 0x45800000, v99
	v_cndmask_b32_e64 v194, v99, v141, s[44:45]
	v_mul_f32_e32 v140, v97, v194
	v_pk_mul_f32 v[154:155], v[78:79], v[140:141] op_sel_hi:[1,0]
	v_pk_mul_f32 v[152:153], v[76:77], v[140:141] op_sel_hi:[1,0]
	v_pk_mul_f32 v[150:151], v[74:75], v[140:141] op_sel_hi:[1,0]
	v_pk_mul_f32 v[148:149], v[72:73], v[140:141] op_sel_hi:[1,0]
	v_pk_mul_f32 v[146:147], v[70:71], v[140:141] op_sel_hi:[1,0]
	v_pk_mul_f32 v[144:145], v[68:69], v[140:141] op_sel_hi:[1,0]
	v_pk_mul_f32 v[142:143], v[66:67], v[140:141] op_sel_hi:[1,0]
	v_pk_mul_f32 v[140:141], v[64:65], v[140:141] op_sel_hi:[1,0]
	s_waitcnt lgkmcnt(4)
	v_pk_add_f32 v[64:65], v[170:171], v[172:173]
	ds_bpermute_b32 v67, v206, v65
	ds_bpermute_b32 v66, v206, v64
	v_mov_b32_e32 v99, v96
	s_waitcnt lgkmcnt(0)
	v_pk_add_f32 v[64:65], v[64:65], v[66:67]
	s_nop 0
	v_pk_fma_f32 v[64:65], v[64:65], s[14:15], v[158:159] op_sel_hi:[1,1,0]
	s_nop 0
	v_mul_f32_e32 v66, 0x4b800000, v65
	v_cmp_gt_f32_e64 s[46:47], s33, v65
	v_cmp_gt_f32_e64 s[44:45], s33, v64
	s_nop 0
	v_cndmask_b32_e64 v65, v65, v66, s[46:47]
	v_rsq_f32_e32 v65, v65
	s_nop 0
	v_mul_f32_e32 v66, 0x45800000, v65
	v_cndmask_b32_e64 v65, v65, v66, s[46:47]
	v_mul_f32_e32 v66, 0x4b800000, v64
	v_cndmask_b32_e64 v66, v64, v66, s[44:45]
	v_rsq_f32_e32 v66, v66
	v_mul_f32_e32 v64, v64, v65
	v_mul_f32_e32 v67, 0x45800000, v66
	v_cndmask_b32_e64 v196, v66, v67, s[44:45]
	v_mul_f32_e32 v64, v64, v196
	v_pk_mul_f32 v[46:47], v[46:47], v[64:65] op_sel_hi:[1,0]
	v_pk_mul_f32 v[44:45], v[44:45], v[64:65] op_sel_hi:[1,0]
	v_pk_mul_f32 v[42:43], v[42:43], v[64:65] op_sel_hi:[1,0]
	v_pk_mul_f32 v[40:41], v[40:41], v[64:65] op_sel_hi:[1,0]
	v_pk_mul_f32 v[38:39], v[38:39], v[64:65] op_sel_hi:[1,0]
	v_pk_mul_f32 v[36:37], v[36:37], v[64:65] op_sel_hi:[1,0]
	v_pk_mul_f32 v[34:35], v[34:35], v[64:65] op_sel_hi:[1,0]
	v_pk_mul_f32 v[32:33], v[32:33], v[64:65] op_sel_hi:[1,0]
	v_pk_add_f32 v[64:65], v[164:165], v[166:167]
	ds_bpermute_b32 v67, v206, v65
	ds_bpermute_b32 v66, v206, v64
	s_waitcnt lgkmcnt(0)
	v_pk_add_f32 v[64:65], v[64:65], v[66:67]
	s_nop 0
	v_pk_fma_f32 v[64:65], v[64:65], s[14:15], v[158:159] op_sel_hi:[1,1,0]
	s_nop 0
	v_mul_f32_e32 v66, 0x4b800000, v65
	v_cmp_gt_f32_e64 s[46:47], s33, v65
	v_cmp_gt_f32_e64 s[44:45], s33, v64
	s_nop 0
	v_cndmask_b32_e64 v65, v65, v66, s[46:47]
	v_rsq_f32_e32 v65, v65
	s_nop 0
	v_mul_f32_e32 v66, 0x45800000, v65
	v_cndmask_b32_e64 v65, v65, v66, s[46:47]
	v_mul_f32_e32 v66, 0x4b800000, v64
	v_cndmask_b32_e64 v66, v64, v66, s[44:45]
	v_rsq_f32_e32 v66, v66
	v_mul_f32_e32 v64, v64, v65
	v_mul_f32_e32 v67, 0x45800000, v66
	v_cndmask_b32_e64 v198, v66, v67, s[44:45]
	v_mul_f32_e32 v64, v64, v198
	v_pk_mul_f32 v[30:31], v[30:31], v[64:65] op_sel_hi:[1,0]
	v_pk_mul_f32 v[28:29], v[28:29], v[64:65] op_sel_hi:[1,0]
	v_pk_mul_f32 v[26:27], v[26:27], v[64:65] op_sel_hi:[1,0]
	v_pk_mul_f32 v[24:25], v[24:25], v[64:65] op_sel_hi:[1,0]
	v_pk_mul_f32 v[22:23], v[22:23], v[64:65] op_sel_hi:[1,0]
	v_pk_mul_f32 v[20:21], v[20:21], v[64:65] op_sel_hi:[1,0]
	v_pk_mul_f32 v[18:19], v[18:19], v[64:65] op_sel_hi:[1,0]
	v_pk_mul_f32 v[16:17], v[16:17], v[64:65] op_sel_hi:[1,0]
	v_pk_add_f32 v[64:65], v[98:99], v[160:161]
	ds_bpermute_b32 v67, v206, v65
	ds_bpermute_b32 v66, v206, v64
	s_waitcnt lgkmcnt(0)
	v_pk_add_f32 v[64:65], v[64:65], v[66:67]
	s_nop 0
	v_pk_fma_f32 v[64:65], v[64:65], s[14:15], v[158:159] op_sel_hi:[1,1,0]
	s_nop 0
	v_mul_f32_e32 v66, 0x4b800000, v65
	v_cmp_gt_f32_e64 s[46:47], s33, v65
	v_cmp_gt_f32_e64 s[44:45], s33, v64
	s_nop 0
	v_cndmask_b32_e64 v65, v65, v66, s[46:47]
	v_rsq_f32_e32 v65, v65
	s_nop 0
	v_mul_f32_e32 v66, 0x45800000, v65
	v_cndmask_b32_e64 v65, v65, v66, s[46:47]
	v_mul_f32_e32 v66, 0x4b800000, v64
	v_cndmask_b32_e64 v66, v64, v66, s[44:45]
	v_rsq_f32_e32 v66, v66
	v_mul_f32_e32 v64, v64, v65
	v_mul_f32_e32 v67, 0x45800000, v66
	v_cndmask_b32_e64 v200, v66, v67, s[44:45]
	v_mul_f32_e32 v64, v64, v200
	v_pk_mul_f32 v[14:15], v[14:15], v[64:65] op_sel_hi:[1,0]
	v_pk_mul_f32 v[12:13], v[12:13], v[64:65] op_sel_hi:[1,0]
	v_pk_mul_f32 v[10:11], v[10:11], v[64:65] op_sel_hi:[1,0]
	v_pk_mul_f32 v[8:9], v[8:9], v[64:65] op_sel_hi:[1,0]
	v_pk_mul_f32 v[6:7], v[6:7], v[64:65] op_sel_hi:[1,0]
	v_pk_mul_f32 v[4:5], v[4:5], v[64:65] op_sel_hi:[1,0]
	v_pk_mul_f32 v[2:3], v[2:3], v[64:65] op_sel_hi:[1,0]
	v_pk_mul_f32 v[0:1], v[0:1], v[64:65] op_sel_hi:[1,0]
	s_mov_b32 s30, 14
	s_mov_b64 s[44:45], 0
